# added: SB output via swapped-operand PV MFMA + permlane32 + 16B stores, unit-1 stores issued after unit-2's K/V loads
# baseline (speedup 1.0000x reference)
.LBB0_355:
	s_ashr_i32 s0, s3, 31
	s_add_u32 s2, s38, s3
	s_addc_u32 s3, s39, s0
	s_lshl_b64 s[2:3], s[2:3], 11
	v_readlane_b32 s0, v255, 22
	s_add_u32 s0, s0, s2
	v_readlane_b32 s2, v255, 23
	s_addc_u32 s3, s2, s3
	s_add_u32 s2, s0, s36
	s_addc_u32 s3, s3, 0
	v_lshlrev_b32_e32 v0, 11, v161
	v_lshl_add_u32 v0, v160, 4, v0
	s_waitcnt vmcnt(0)
	v_lshl_add_u64 v[2:3], s[2:3], 0, v[0:1]
	v_cvt_pk_bf16_f32 v50, v50, v51
	v_cvt_pk_bf16_f32 v51, v52, v53
	v_cvt_pk_bf16_f32 v52, v54, v55
	v_cvt_pk_bf16_f32 v53, v56, v57
	v_cvt_pk_bf16_f32 v54, v58, v59
	v_cvt_pk_bf16_f32 v55, v60, v61
	v_cvt_pk_bf16_f32 v56, v62, v63
	v_cvt_pk_bf16_f32 v57, v64, v65
	v_cvt_pk_bf16_f32 v66, v66, v67
	v_cvt_pk_bf16_f32 v67, v68, v69
	v_cvt_pk_bf16_f32 v68, v70, v71
	v_cvt_pk_bf16_f32 v69, v72, v73
	v_cvt_pk_bf16_f32 v70, v74, v75
	v_cvt_pk_bf16_f32 v71, v76, v77
	v_cvt_pk_bf16_f32 v72, v78, v79
	v_cvt_pk_bf16_f32 v73, v80, v81
	s_nop 1
	v_permlane32_swap_b32_e32 v50, v52
	v_permlane32_swap_b32_e32 v51, v53
	v_permlane32_swap_b32_e32 v54, v56
	v_permlane32_swap_b32_e32 v55, v57
	v_permlane32_swap_b32_e32 v66, v68
	v_permlane32_swap_b32_e32 v67, v69
	v_permlane32_swap_b32_e32 v70, v72
	v_permlane32_swap_b32_e32 v71, v73
	global_store_dwordx4 v[2:3], v[50:53], off
	global_store_dwordx4 v[2:3], v[54:57], off offset:32
	global_store_dwordx4 v[2:3], v[66:69], off offset:64
	global_store_dwordx4 v[2:3], v[70:73], off offset:96
	s_nop 1
	v_readlane_b32 s92, v254, 42
	v_readlane_b32 s94, v254, 44
	s_add_i32 s19, s19, s94
	s_add_i32 s18, s18, s94
	v_readlane_b32 s93, v254, 43
	s_cmpk_lt_i32 s19, 0x400
	v_readlane_b32 s95, v254, 45
	s_cbranch_scc0 .LBB0_353

.LBB0_359:
	s_add_i32 s29, s24, s25
	s_cmp_lt_i32 s29, 0
	s_cselect_b64 s[36:37], -1, 0
	s_or_b64 s[36:37], s[36:37], s[30:31]
	s_and_b64 vcc, exec, s[36:37]
	s_cbranch_vccnz .LBB0_364
	s_mul_hi_u32 s25, s14, 0xcccccccd
	s_lshr_b32 s25, s25, 2
	s_mul_i32 s26, s25, 0xf000
	s_mul_i32 s25, s25, 0xb400
	v_subrev_u32_e32 v10, s25, v179
	v_subrev_u32_e32 v0, s26, v155
	v_subrev_u32_e32 v189, s26, v162
	v_subrev_u32_e32 v190, s26, v163
	v_subrev_u32_e32 v191, s26, v164
	v_subrev_u32_e32 v192, s26, v165
	v_subrev_u32_e32 v193, s26, v166
	v_subrev_u32_e32 v194, s26, v167
	v_subrev_u32_e32 v196, s26, v168
	v_subrev_u32_e32 v197, s26, v169
	v_subrev_u32_e32 v210, s26, v170
	v_subrev_u32_e32 v211, s26, v171
	v_subrev_u32_e32 v212, s26, v172
	v_subrev_u32_e32 v213, s26, v173
	v_subrev_u32_e32 v214, s26, v174
	v_subrev_u32_e32 v215, s26, v175
	v_subrev_u32_e32 v216, s26, v176
	s_cmp_lg_u32 s35, 0
	v_add_u32_e32 v217, 0, v10
	s_cbranch_scc0 .LBB0_365
	ds_read_b128 v[50:53], v217 offset:4608
	ds_read_b128 v[70:73], v217 offset:4640
	ds_read_b128 v[66:69], v217
	ds_read_b128 v[84:87], v217 offset:32
	ds_read_b128 v[74:77], v217 offset:4672
	ds_read_b128 v[88:91], v217 offset:4704
	ds_read_b128 v[80:83], v217 offset:64
	ds_read_b128 v[10:13], v217 offset:96
	s_waitcnt lgkmcnt(7)
	v_mfma_f32_32x32x16_bf16 v[50:65], v[50:53], v[130:133], 0
	s_waitcnt lgkmcnt(6)
	v_mfma_f32_32x32x16_bf16 v[50:65], v[70:73], v[134:137], v[50:65]
	s_waitcnt lgkmcnt(3)
	v_mfma_f32_32x32x16_bf16 v[50:65], v[74:77], v[138:141], v[50:65]
	s_waitcnt lgkmcnt(2)
	v_mfma_f32_32x32x16_bf16 v[50:65], v[88:91], v[142:145], v[50:65]
	s_nop 11
	v_max_f32_e32 v14, v50, v50
	v_min_f32_e32 v14, 0x42fc0000, v14
	v_exp_f32_e32 v15, v14
	s_nop 0
	v_add_f32_e32 v15, 1.0, v15
	v_log_f32_e32 v49, v15
	v_max_f32_e32 v15, v51, v51
	v_max_f32_e32 v51, v52, v52
	v_min_f32_e32 v51, 0x42fc0000, v51
	v_exp_f32_e32 v52, v51
	v_min_f32_e32 v15, 0x42fc0000, v15
	v_exp_f32_e32 v50, v15
	v_sub_f32_e32 v14, v14, v49
	v_add_f32_e32 v52, 1.0, v52
	v_log_f32_e32 v52, v52
	v_add_f32_e32 v50, 1.0, v50
	v_log_f32_e32 v50, v50
	v_sub_f32_e32 v218, v51, v52
	v_max_f32_e32 v51, v53, v53
	v_min_f32_e32 v51, 0x42fc0000, v51
	v_exp_f32_e32 v53, v51
	v_sub_f32_e32 v15, v15, v50
	v_add_f32_e32 v53, 1.0, v53
	v_log_f32_e32 v53, v53
	s_nop 0
	v_sub_f32_e32 v219, v51, v53
	v_max_f32_e32 v51, v54, v54
	v_min_f32_e32 v51, 0x42fc0000, v51
	v_exp_f32_e32 v54, v51
	s_nop 0
	v_add_f32_e32 v54, 1.0, v54
	v_log_f32_e32 v54, v54
	s_nop 0
	v_sub_f32_e32 v220, v51, v54
	v_max_f32_e32 v51, v55, v55
	v_min_f32_e32 v51, 0x42fc0000, v51
	v_exp_f32_e32 v55, v51
	s_nop 0
	v_add_f32_e32 v55, 1.0, v55
	v_log_f32_e32 v55, v55
	s_nop 0
	v_sub_f32_e32 v221, v51, v55
	v_max_f32_e32 v51, v56, v56
	v_min_f32_e32 v51, 0x42fc0000, v51
	v_exp_f32_e32 v56, v51
	s_nop 0
	v_add_f32_e32 v56, 1.0, v56
	v_log_f32_e32 v56, v56
	s_nop 0
	v_sub_f32_e32 v222, v51, v56
	v_max_f32_e32 v51, v57, v57
	v_min_f32_e32 v51, 0x42fc0000, v51
	v_exp_f32_e32 v57, v51
	s_nop 0
	v_add_f32_e32 v57, 1.0, v57
	v_log_f32_e32 v57, v57
	s_nop 0
	v_sub_f32_e32 v223, v51, v57
	v_max_f32_e32 v51, v58, v58
	v_min_f32_e32 v51, 0x42fc0000, v51
	v_exp_f32_e32 v58, v51
	s_nop 0
	v_add_f32_e32 v58, 1.0, v58
	v_log_f32_e32 v58, v58
	s_nop 0
	v_sub_f32_e32 v224, v51, v58
	v_max_f32_e32 v51, v59, v59
	v_min_f32_e32 v51, 0x42fc0000, v51
	v_exp_f32_e32 v59, v51
	s_nop 0
	v_add_f32_e32 v59, 1.0, v59
	v_log_f32_e32 v59, v59
	s_nop 0
	v_sub_f32_e32 v225, v51, v59
	v_max_f32_e32 v51, v60, v60
	v_min_f32_e32 v51, 0x42fc0000, v51
	v_exp_f32_e32 v60, v51
	s_nop 0
	v_add_f32_e32 v60, 1.0, v60
	v_log_f32_e32 v60, v60
	s_nop 0
	v_sub_f32_e32 v226, v51, v60
	v_max_f32_e32 v51, v61, v61
	v_min_f32_e32 v51, 0x42fc0000, v51
	v_exp_f32_e32 v61, v51
	s_nop 0
	v_add_f32_e32 v61, 1.0, v61
	v_log_f32_e32 v61, v61
	s_nop 0
	v_sub_f32_e32 v227, v51, v61
	v_max_f32_e32 v51, v62, v62
	v_min_f32_e32 v51, 0x42fc0000, v51
	v_exp_f32_e32 v62, v51
	s_nop 0
	v_add_f32_e32 v62, 1.0, v62
	v_log_f32_e32 v62, v62
	s_nop 0
	v_sub_f32_e32 v228, v51, v62
	v_max_f32_e32 v51, v63, v63
	v_min_f32_e32 v51, 0x42fc0000, v51
	v_exp_f32_e32 v63, v51
	s_nop 0
	v_add_f32_e32 v63, 1.0, v63
	v_log_f32_e32 v63, v63
	s_nop 0
	v_sub_f32_e32 v229, v51, v63
	v_max_f32_e32 v51, v64, v64
	v_min_f32_e32 v51, 0x42fc0000, v51
	v_exp_f32_e32 v64, v51
	s_nop 0
	v_add_f32_e32 v64, 1.0, v64
	v_log_f32_e32 v88, v64
	s_nop 0
	v_sub_f32_e32 v230, v51, v88
	v_max_f32_e32 v51, v65, v65
	v_min_f32_e32 v51, 0x42fc0000, v51
	v_exp_f32_e32 v64, v51
	s_nop 0
	v_add_f32_e32 v64, 1.0, v64
	v_log_f32_e32 v89, v64
	v_mfma_f32_32x32x16_bf16 v[64:79], v[66:69], v[130:133], 0
	v_sub_f32_e32 v231, v51, v89
	v_mov_b32_e32 v51, v48
	v_mfma_f32_32x32x16_bf16 v[64:79], v[84:87], v[134:137], v[64:79]
	v_cvt_pk_bf16_f32 v86, v62, v63
	v_mov_b32_e32 v62, v48
	v_mov_b32_e32 v63, v48
	v_cvt_pk_bf16_f32 v84, v58, v59
	v_cvt_pk_bf16_f32 v85, v60, v61
	v_mov_b32_e32 v58, v48
	v_mov_b32_e32 v59, v48
	s_waitcnt lgkmcnt(1)
	v_mfma_f32_32x32x16_bf16 v[64:79], v[80:83], v[138:141], v[64:79]
	v_cvt_pk_bf16_f32 v80, v49, v50
	v_cvt_pk_bf16_f32 v81, v52, v53
	v_cvt_pk_bf16_f32 v82, v54, v55
	v_cvt_pk_bf16_f32 v83, v56, v57
	v_mov_b32_e32 v49, v48
	v_mov_b32_e32 v50, v48
	v_mov_b32_e32 v52, v48
	v_mov_b32_e32 v53, v48
	v_mov_b32_e32 v54, v48
	v_mov_b32_e32 v55, v48
	v_mov_b32_e32 v56, v48
	v_mov_b32_e32 v57, v48
	v_mov_b32_e32 v60, v48
	v_mov_b32_e32 v61, v48
	v_mov_b64_e32 v[112:113], v[62:63]
	v_mov_b64_e32 v[110:111], v[60:61]
	v_mov_b64_e32 v[108:109], v[58:59]
	v_mov_b64_e32 v[106:107], v[56:57]
	v_mov_b64_e32 v[104:105], v[54:55]
	v_mov_b64_e32 v[102:103], v[52:53]
	v_mov_b64_e32 v[100:101], v[50:51]
	v_mov_b64_e32 v[98:99], v[48:49]
	v_cvt_pk_bf16_f32 v87, v88, v89
	s_waitcnt lgkmcnt(0)
	v_mfma_f32_32x32x16_bf16 v[64:79], v[10:13], v[142:145], v[64:79]
	v_mfma_f32_32x32x16_bf16 v[98:113], v[146:149], v[80:83], v[98:113]
	v_mfma_f32_32x32x16_bf16 v[98:113], v[150:153], v[84:87], v[98:113]
	s_nop 9
	v_max_f32_e32 v10, v64, v64
	v_min_f32_e32 v232, 0x42fc0000, v10
	v_max_f32_e32 v11, v65, v65
	v_exp_f32_e32 v10, v232
	v_min_f32_e32 v233, 0x42fc0000, v11
	v_exp_f32_e32 v11, v233
	v_max_f32_e32 v12, v67, v67
	v_add_f32_e32 v10, 1.0, v10
	v_log_f32_e32 v234, v10
	v_add_f32_e32 v10, 1.0, v11
	v_max_f32_e32 v11, v66, v66
	v_min_f32_e32 v235, 0x42fc0000, v11
	v_exp_f32_e32 v11, v235
	v_min_f32_e32 v236, 0x42fc0000, v12
	v_exp_f32_e32 v12, v236
	v_log_f32_e32 v237, v10
	v_add_f32_e32 v10, 1.0, v11
	v_max_f32_e32 v11, v68, v68
	v_log_f32_e32 v238, v10
	v_add_f32_e32 v10, 1.0, v12
	v_min_f32_e32 v239, 0x42fc0000, v11
	v_max_f32_e32 v12, v69, v69
	v_exp_f32_e32 v11, v239
	v_min_f32_e32 v240, 0x42fc0000, v12
	v_exp_f32_e32 v12, v240
	v_log_f32_e32 v241, v10
	v_add_f32_e32 v10, 1.0, v11
	v_max_f32_e32 v11, v70, v70
	v_log_f32_e32 v242, v10
	v_add_f32_e32 v10, 1.0, v12
	v_min_f32_e32 v243, 0x42fc0000, v11
	v_max_f32_e32 v12, v71, v71
	v_exp_f32_e32 v11, v243
	v_min_f32_e32 v244, 0x42fc0000, v12
	v_exp_f32_e32 v12, v244
	v_log_f32_e32 v245, v10
	v_add_f32_e32 v10, 1.0, v11
	v_max_f32_e32 v11, v72, v72
	v_log_f32_e32 v246, v10
	v_add_f32_e32 v10, 1.0, v12
	v_min_f32_e32 v247, 0x42fc0000, v11
	v_max_f32_e32 v12, v73, v73
	v_exp_f32_e32 v11, v247
	v_min_f32_e32 v248, 0x42fc0000, v12
	v_exp_f32_e32 v12, v248
	v_log_f32_e32 v249, v10
	v_add_f32_e32 v10, 1.0, v11
	v_max_f32_e32 v11, v74, v74
	v_log_f32_e32 v250, v10
	v_add_f32_e32 v10, 1.0, v12
	v_min_f32_e32 v251, 0x42fc0000, v11
	v_max_f32_e32 v12, v75, v75
	v_exp_f32_e32 v11, v251
	v_min_f32_e32 v202, 0x42fc0000, v12
	v_exp_f32_e32 v12, v202
	v_log_f32_e32 v203, v10
	v_add_f32_e32 v10, 1.0, v11
	v_max_f32_e32 v11, v76, v76
	v_log_f32_e32 v199, v10
	v_add_f32_e32 v10, 1.0, v12
	v_min_f32_e32 v207, 0x42fc0000, v11
	v_max_f32_e32 v12, v77, v77
	v_exp_f32_e32 v11, v207
	v_min_f32_e32 v201, 0x42fc0000, v12
	v_exp_f32_e32 v12, v201
	v_log_f32_e32 v186, v10
	v_add_f32_e32 v10, 1.0, v11
	v_max_f32_e32 v11, v78, v78
	v_log_f32_e32 v187, v10
	v_add_f32_e32 v10, 1.0, v12
	v_min_f32_e32 v198, 0x42fc0000, v11
	v_max_f32_e32 v12, v79, v79
	v_exp_f32_e32 v11, v198
	v_min_f32_e32 v208, 0x42fc0000, v12
	v_exp_f32_e32 v12, v208
	v_log_f32_e32 v184, v10
	v_add_f32_e32 v10, 1.0, v11
	v_log_f32_e32 v185, v10
	v_add_f32_e32 v10, 1.0, v12
	v_log_f32_e32 v180, v10
	v_cvt_pk_bf16_f32 v12, v242, v245
	v_cvt_pk_bf16_f32 v13, v246, v249
	v_cvt_pk_bf16_f32 v50, v250, v203
	v_cvt_pk_bf16_f32 v51, v199, v186
	v_cvt_pk_bf16_f32 v52, v187, v184
	v_cvt_pk_bf16_f32 v53, v185, v180
	v_cvt_pk_bf16_f32 v10, v234, v237
	v_cvt_pk_bf16_f32 v11, v238, v241
	v_lshlrev_b32_e32 v49, 16, v80
	v_add_f32_e32 v49, v98, v49
	ds_bpermute_b32 v114, v188, v49
	s_add_i32 s25, s15, s17
	v_add_u32_e32 v49, s25, v212
	s_waitcnt lgkmcnt(0)
	v_mov_b32_e32 v115, v114
	v_mov_b32_e32 v116, v114
	v_mov_b32_e32 v117, v114
	v_mov_b32_e32 v118, v114
	v_mov_b32_e32 v119, v114
	v_mov_b32_e32 v120, v114
	v_mov_b32_e32 v121, v114
	v_mov_b32_e32 v122, v114
	v_mov_b32_e32 v123, v114
	v_mov_b32_e32 v124, v114
	v_mov_b32_e32 v125, v114
	v_mov_b32_e32 v126, v114
	v_mov_b32_e32 v127, v114
	v_mov_b32_e32 v128, v114
	v_mov_b32_e32 v129, v114
	v_mov_b64_e32 v[82:83], v[114:115]
	v_mov_b64_e32 v[84:85], v[116:117]
	v_mov_b64_e32 v[86:87], v[118:119]
	v_mov_b64_e32 v[88:89], v[120:121]
	v_mov_b64_e32 v[90:91], v[122:123]
	v_mov_b64_e32 v[92:93], v[124:125]
	v_mov_b64_e32 v[94:95], v[126:127]
	v_mov_b64_e32 v[96:97], v[128:129]
	s_nop 1
	v_mfma_f32_32x32x16_bf16 v[82:97], v[146:149], v[10:13], v[82:97]
	v_add_u32_e32 v12, s25, v196
	ds_read_b64_tr_b16 v[66:67], v12
	v_add_u32_e32 v12, s25, v194
	ds_read_b64_tr_b16 v[68:69], v12
	v_add_u32_e32 v12, s25, v193
	ds_read_b64_tr_b16 v[116:117], v12
	v_add_u32_e32 v12, s25, v192
	v_mfma_f32_32x32x16_bf16 v[82:97], v[150:153], v[50:53], v[82:97]
	ds_read_b64_tr_b16 v[118:119], v12
	v_add_u32_e32 v12, s25, v191
	ds_read_b64_tr_b16 v[120:121], v12
	v_add_u32_e32 v12, s25, v190
	ds_read_b64_tr_b16 v[122:123], v12
	v_add_u32_e32 v12, s25, v189
	ds_read_b64_tr_b16 v[124:125], v12
	v_add_u32_e32 v12, s25, v0
	ds_read_b64_tr_b16 v[126:127], v12
	v_add_u32_e32 v11, s25, v216
	v_sub_f32_e32 v12, v14, v98
	v_sub_f32_e32 v13, v15, v99
	v_sub_f32_e32 v14, v218, v100
	v_sub_f32_e32 v15, v219, v101
	v_sub_f32_e32 v50, v220, v102
	v_sub_f32_e32 v51, v221, v103
	v_sub_f32_e32 v52, v222, v104
	v_sub_f32_e32 v53, v223, v105
	v_sub_f32_e32 v54, v224, v106
	v_sub_f32_e32 v55, v225, v107
	v_sub_f32_e32 v56, v226, v108
	v_sub_f32_e32 v57, v227, v109
	v_sub_f32_e32 v58, v228, v110
	v_sub_f32_e32 v59, v229, v111
	v_sub_f32_e32 v60, v230, v112
	v_sub_f32_e32 v61, v231, v113
	v_exp_f32_e32 v12, v12
	v_exp_f32_e32 v13, v13
	v_exp_f32_e32 v14, v14
	v_exp_f32_e32 v15, v15
	v_exp_f32_e32 v50, v50
	v_exp_f32_e32 v51, v51
	v_exp_f32_e32 v52, v52
	v_exp_f32_e32 v53, v53
	v_exp_f32_e32 v54, v54
	v_exp_f32_e32 v55, v55
	v_exp_f32_e32 v56, v56
	v_exp_f32_e32 v57, v57
	v_exp_f32_e32 v58, v58
	v_exp_f32_e32 v59, v59
	v_exp_f32_e32 v60, v60
	v_exp_f32_e32 v61, v61
	v_cvt_pk_bf16_f32 v12, v12, v13
	v_cvt_pk_bf16_f32 v13, v14, v15
	v_cvt_pk_bf16_f32 v14, v50, v51
	v_cvt_pk_bf16_f32 v15, v52, v53
	v_cvt_pk_bf16_f32 v98, v54, v55
	v_cvt_pk_bf16_f32 v99, v56, v57
	v_cvt_pk_bf16_f32 v100, v58, v59
	v_cvt_pk_bf16_f32 v101, v60, v61
	s_waitcnt lgkmcnt(6)
	v_mfma_f32_32x32x16_bf16 v[50:65], v[66:69], v[12:15], v[32:47]
	ds_read_b64_tr_b16 v[102:103], v11
	v_add_u32_e32 v11, s25, v215
	ds_read_b64_tr_b16 v[104:105], v11
	v_add_u32_e32 v11, s25, v214
	s_waitcnt lgkmcnt(6)
	v_mfma_f32_32x32x16_bf16 v[66:81], v[116:119], v[12:15], v[16:31]
	s_waitcnt lgkmcnt(4)
	v_mfma_f32_32x32x16_bf16 v[50:65], v[120:123], v[98:101], v[50:65]
	s_waitcnt lgkmcnt(2)
	v_mfma_f32_32x32x16_bf16 v[66:81], v[124:127], v[98:101], v[66:81]
	ds_read_b64_tr_b16 v[98:99], v11
	v_add_u32_e32 v11, s25, v213
	ds_read_b64_tr_b16 v[100:101], v11
	ds_read_b64_tr_b16 v[12:13], v49
	v_add_u32_e32 v11, s25, v211
	ds_read_b64_tr_b16 v[14:15], v11
	v_add_u32_e32 v11, s25, v210
	ds_read_b64_tr_b16 v[106:107], v11
	v_add_u32_e32 v11, s25, v197
	ds_read_b64_tr_b16 v[108:109], v11
	v_lshlrev_b32_e32 v10, 16, v10
	v_add_f32_e32 v10, v82, v10
	ds_bpermute_b32 v49, v188, v10
	v_cmp_lt_f32_e32 vcc, s33, v114
	s_cmp_eq_u64 vcc, exec
	s_cbranch_scc1 .LBB0_363
	v_sub_f32_e32 v10, v232, v234
	v_sub_f32_e32 v110, v235, v238
	v_sub_f32_e32 v11, v233, v237
	v_sub_f32_e32 v111, v236, v241
	v_sub_f32_e32 v10, v10, v82
	v_sub_f32_e32 v82, v110, v84
	v_sub_f32_e32 v112, v239, v242
	v_sub_f32_e32 v11, v11, v83
	v_exp_f32_e32 v83, v82
	v_sub_f32_e32 v82, v111, v85
	v_sub_f32_e32 v113, v240, v245
	v_exp_f32_e32 v84, v82
	v_sub_f32_e32 v82, v112, v86
	v_sub_f32_e32 v114, v243, v246
	v_exp_f32_e32 v85, v82
	v_sub_f32_e32 v82, v113, v87
	v_sub_f32_e32 v115, v244, v249
	v_exp_f32_e32 v86, v82
	v_sub_f32_e32 v82, v114, v88
	v_sub_f32_e32 v116, v247, v250
	v_exp_f32_e32 v87, v82
	v_sub_f32_e32 v82, v115, v89
	v_sub_f32_e32 v117, v248, v203
	v_exp_f32_e32 v88, v82
	v_sub_f32_e32 v82, v116, v90
	v_sub_f32_e32 v118, v251, v199
	v_exp_f32_e32 v89, v82
	v_sub_f32_e32 v82, v117, v91
	v_sub_f32_e32 v119, v202, v186
	v_exp_f32_e32 v90, v82
	v_sub_f32_e32 v82, v118, v92
	v_sub_f32_e32 v120, v207, v187
	v_exp_f32_e32 v91, v82
	v_sub_f32_e32 v82, v119, v93
	v_sub_f32_e32 v121, v201, v184
	v_exp_f32_e32 v10, v10
	v_exp_f32_e32 v11, v11
	v_exp_f32_e32 v92, v82
	v_sub_f32_e32 v82, v120, v94
	v_sub_f32_e32 v122, v198, v185
	v_exp_f32_e32 v93, v82
	v_sub_f32_e32 v82, v121, v95
	v_sub_f32_e32 v123, v208, v180
	v_exp_f32_e32 v94, v82
	v_sub_f32_e32 v82, v122, v96
	v_exp_f32_e32 v95, v82
	v_sub_f32_e32 v82, v123, v97
	v_exp_f32_e32 v96, v82
	v_cvt_pk_bf16_f32 v82, v10, v11
	v_cvt_pk_bf16_f32 v83, v83, v84
	v_cvt_pk_bf16_f32 v84, v85, v86
	v_cvt_pk_bf16_f32 v85, v87, v88
	v_cvt_pk_bf16_f32 v86, v89, v90
	v_cvt_pk_bf16_f32 v87, v91, v92
	s_waitcnt lgkmcnt(7)
	v_mfma_f32_32x32x16_bf16 v[50:65], v[102:105], v[82:85], v[50:65]
	v_cvt_pk_bf16_f32 v88, v93, v94
	v_cvt_pk_bf16_f32 v89, v95, v96
	s_waitcnt lgkmcnt(5)
	v_mfma_f32_32x32x16_bf16 v[66:81], v[98:101], v[82:85], v[66:81]
	s_waitcnt lgkmcnt(3)
	v_mfma_f32_32x32x16_bf16 v[50:65], v[12:15], v[86:89], v[50:65]
	s_waitcnt lgkmcnt(1)
	v_mfma_f32_32x32x16_bf16 v[66:81], v[106:109], v[86:89], v[66:81]

.LBB0_372:
	s_add_i32 s25, s15, s17
	s_waitcnt lgkmcnt(3)
	v_add_u32_e32 v14, s25, v216
	v_add_u32_e32 v64, s25, v213
	v_add_u32_e32 v15, s25, v215
	v_add_u32_e32 v48, s25, v214
	ds_read_b64_tr_b16 v[58:59], v14
	ds_read_b64_tr_b16 v[60:61], v15
	ds_read_b64_tr_b16 v[62:63], v48
	ds_read_b64_tr_b16 v[64:65], v64
	v_add_u32_e32 v14, s25, v212
	v_add_u32_e32 v76, s25, v197
	v_add_u32_e32 v15, s25, v211
	v_add_u32_e32 v48, s25, v210
	ds_read_b64_tr_b16 v[70:71], v14
	ds_read_b64_tr_b16 v[72:73], v15
	ds_read_b64_tr_b16 v[74:75], v48
	ds_read_b64_tr_b16 v[76:77], v76
	v_add_u32_e32 v14, s25, v196
	v_add_u32_e32 v84, s25, v192
	v_add_u32_e32 v15, s25, v194
	v_add_u32_e32 v48, s25, v193
	ds_read_b64_tr_b16 v[78:79], v14
	ds_read_b64_tr_b16 v[80:81], v15
	ds_read_b64_tr_b16 v[82:83], v48
	ds_read_b64_tr_b16 v[84:85], v84
	v_add_u32_e32 v14, s25, v191
	v_add_u32_e32 v15, s25, v190
	v_add_u32_e32 v48, s25, v189
	v_add_u32_e32 v0, s25, v0
	ds_read_b64_tr_b16 v[86:87], v14
	ds_read_b64_tr_b16 v[88:89], v15
	ds_read_b64_tr_b16 v[90:91], v48
	ds_read_b64_tr_b16 v[92:93], v0
	s_waitcnt lgkmcnt(14)
	v_mfma_f32_32x32x16_bf16 v[32:47], v[58:61], v[54:57], v[32:47]
	s_waitcnt lgkmcnt(12)
	v_mfma_f32_32x32x16_bf16 v[16:31], v[62:65], v[54:57], v[16:31]
	s_waitcnt lgkmcnt(10)
	v_mfma_f32_32x32x16_bf16 v[32:47], v[70:73], v[50:53], v[32:47]
	s_waitcnt lgkmcnt(8)
	v_mfma_f32_32x32x16_bf16 v[16:31], v[74:77], v[50:53], v[16:31]
	s_waitcnt lgkmcnt(6)
	v_mfma_f32_32x32x16_bf16 v[32:47], v[78:81], v[66:69], v[32:47]
	s_waitcnt lgkmcnt(4)
	v_mfma_f32_32x32x16_bf16 v[16:31], v[82:85], v[66:69], v[16:31]
	s_waitcnt lgkmcnt(2)
	v_mfma_f32_32x32x16_bf16 v[32:47], v[86:89], v[10:13], v[32:47]
	s_waitcnt lgkmcnt(0)
	v_mfma_f32_32x32x16_bf16 v[16:31], v[90:93], v[10:13], v[16:31]
	s_nop 9
	v_mov_b64_e32 v[64:65], v[46:47]
	v_mov_b64_e32 v[62:63], v[44:45]
	v_mov_b64_e32 v[60:61], v[42:43]
	v_mov_b64_e32 v[58:59], v[40:41]
	v_mov_b64_e32 v[56:57], v[38:39]
	v_mov_b64_e32 v[54:55], v[36:37]
	v_mov_b64_e32 v[52:53], v[34:35]
	v_mov_b64_e32 v[80:81], v[30:31]
	v_mov_b64_e32 v[50:51], v[32:33]
	v_mov_b64_e32 v[78:79], v[28:29]
	v_mov_b64_e32 v[76:77], v[26:27]
	v_mov_b64_e32 v[74:75], v[24:25]
	v_mov_b64_e32 v[72:73], v[22:23]
	v_mov_b64_e32 v[70:71], v[20:21]
	v_mov_b64_e32 v[68:69], v[18:19]
	v_mov_b64_e32 v[66:67], v[16:17]

.LBB0_379:
	s_ashr_i32 s0, s28, 31
	s_add_u32 s4, s38, s28
	s_addc_u32 s5, s39, s0
	s_lshl_b64 s[4:5], s[4:5], 11
	v_readlane_b32 s0, v255, 22
	s_add_u32 s0, s0, s4
	v_readlane_b32 s2, v255, 23
	s_addc_u32 s4, s2, s5
	s_lshl_b32 s36, s3, 1
	s_add_u32 s2, s0, s36
	s_addc_u32 s3, s4, 0
	s_mov_b64 s[100:101], s[2:3]
	v_mov_b32_e32 v41, v195
	s_xor_b32 s12, s16, 15
	v_readlane_b32 s6, v255, 20
	v_readlane_b32 s7, v255, 21
	s_lshl_b32 s0, s12, 8
	v_readfirstlane_b32 s2, v41
	s_ashr_i32 s4, s2, 6
	s_lshl_b32 s3, s4, 5
	v_ashrrev_i32_e32 v2, 3, v41
	v_and_b32_e32 v161, 31, v41
	s_add_i32 s3, s3, s0
	v_ashrrev_i32_e32 v3, 31, v2
	v_or_b32_e32 v154, s3, v161
	v_lshl_add_u64 v[4:5], s[38:39], 0, v[2:3]
	v_lshlrev_b64 v[6:7], 11, v[4:5]
	v_ashrrev_i32_e32 v155, 31, v154
	v_lshl_add_u64 v[4:5], s[6:7], 0, v[6:7]
	v_lshl_add_u64 v[10:11], s[38:39], 0, v[154:155]
	v_readlane_b32 s6, v255, 16
	v_lshlrev_b64 v[10:11], 11, v[10:11]
	v_readlane_b32 s7, v255, 17
	s_mov_b32 s37, s1
	v_bfe_u32 v160, v41, 5, 1
	v_lshl_add_u64 v[10:11], s[6:7], 0, v[10:11]
	v_readlane_b32 s6, v255, 18
	v_readlane_b32 s7, v255, 19
	s_lshl_b32 s24, s12, 2
	v_lshlrev_b32_e32 v0, 4, v41
	v_lshl_add_u64 v[6:7], s[6:7], 0, v[6:7]
	v_lshl_add_u64 v[8:9], v[4:5], 0, s[36:37]
	v_and_b32_e32 v4, 0x70, v0
	v_lshl_add_u64 v[10:11], v[10:11], 0, s[36:37]
	v_lshlrev_b32_e32 v0, 4, v160
	s_or_b32 s5, s24, 3
	v_lshl_add_u64 v[6:7], v[6:7], 0, s[36:37]
	v_mov_b32_e32 v5, v1
	v_lshl_add_u64 v[10:11], v[10:11], 0, v[0:1]
	v_lshl_add_u64 v[156:157], v[6:7], 0, v[4:5]
	v_lshl_add_u64 v[158:159], v[8:9], 0, v[4:5]
	s_lshl_b32 s0, s5, 17
	s_or_b32 s8, s24, 2
	global_load_dwordx4 v[130:133], v[10:11], off
	global_load_dwordx4 v[134:137], v[10:11], off offset:32
	global_load_dwordx4 v[138:141], v[10:11], off offset:64
	global_load_dwordx4 v[142:145], v[10:11], off offset:96
	v_lshl_add_u64 v[6:7], v[156:157], 0, s[0:1]
	v_lshl_add_u64 v[10:11], v[158:159], 0, s[0:1]
	s_lshl_b32 s0, s8, 17
	s_or_b32 s9, s24, 1
	v_lshl_add_u64 v[14:15], v[156:157], 0, s[0:1]
	v_lshl_add_u64 v[18:19], v[158:159], 0, s[0:1]
	s_lshl_b32 s0, s9, 17
	v_lshl_add_u64 v[22:23], v[156:157], 0, s[0:1]
	v_lshl_add_u64 v[26:27], v[158:159], 0, s[0:1]
	s_lshl_b32 s0, s12, 19
	v_lshl_add_u64 v[30:31], v[156:157], 0, s[0:1]
	v_lshl_add_u64 v[34:35], v[158:159], 0, s[0:1]
	global_load_dwordx4 v[6:9], v[6:7], off
	s_nop 0
	global_load_dwordx4 v[10:13], v[10:11], off
	s_nop 0
	global_load_dwordx4 v[14:17], v[14:15], off
	s_nop 0
	global_load_dwordx4 v[18:21], v[18:19], off
	s_nop 0
	global_load_dwordx4 v[22:25], v[22:23], off
	s_nop 0
	global_load_dwordx4 v[26:29], v[26:27], off
	s_nop 0
	global_load_dwordx4 v[30:33], v[30:31], off
	s_nop 0
	global_load_dwordx4 v[34:37], v[34:35], off
	v_lshlrev_b32_e32 v38, 11, v161
	v_lshl_add_u32 v38, v160, 4, v38
	v_mov_b32_e32 v39, 0
	v_lshl_add_u64 v[38:39], v[38:39], 0, s[100:101]
	v_cvt_pk_bf16_f32 v50, v50, v51
	v_cvt_pk_bf16_f32 v51, v52, v53
	v_cvt_pk_bf16_f32 v52, v54, v55
	v_cvt_pk_bf16_f32 v53, v56, v57
	v_cvt_pk_bf16_f32 v54, v58, v59
	v_cvt_pk_bf16_f32 v55, v60, v61
	v_cvt_pk_bf16_f32 v56, v62, v63
	v_cvt_pk_bf16_f32 v57, v64, v65
	v_cvt_pk_bf16_f32 v66, v66, v67
	v_cvt_pk_bf16_f32 v67, v68, v69
	v_cvt_pk_bf16_f32 v68, v70, v71
	v_cvt_pk_bf16_f32 v69, v72, v73
	v_cvt_pk_bf16_f32 v70, v74, v75
	v_cvt_pk_bf16_f32 v71, v76, v77
	v_cvt_pk_bf16_f32 v72, v78, v79
	v_cvt_pk_bf16_f32 v73, v80, v81
	s_nop 1
	v_permlane32_swap_b32_e32 v50, v52
	v_permlane32_swap_b32_e32 v51, v53
	v_permlane32_swap_b32_e32 v54, v56
	v_permlane32_swap_b32_e32 v55, v57
	v_permlane32_swap_b32_e32 v66, v68
	v_permlane32_swap_b32_e32 v67, v69
	v_permlane32_swap_b32_e32 v70, v72
	v_permlane32_swap_b32_e32 v71, v73
	global_store_dwordx4 v[38:39], v[50:53], off
	global_store_dwordx4 v[38:39], v[54:57], off offset:32
	global_store_dwordx4 v[38:39], v[66:69], off offset:64
	global_store_dwordx4 v[38:39], v[70:73], off offset:96
	s_nop 1
	s_movk_i32 s0, 0xc0
	v_mad_u64_u32 v[38:39], s[6:7], v2, s0, v[4:5]
	v_add_u32_e32 v40, 0, v38
	s_movk_i32 s0, 0xffd0
	v_mad_u64_u32 v[42:43], s[6:7], v2, s0, v[40:41]
	v_lshlrev_b32_e32 v5, 2, v160
	v_cmp_gt_u32_e32 vcc, v5, v161
	v_or_b32_e32 v43, 16, v5
	s_mov_b32 s13, 0x5040100
	v_cndmask_b32_e32 v39, 0, v205, vcc
	v_cmp_gt_u32_e32 vcc, v43, v161
	v_or_b32_e32 v46, 2, v5
	v_or_b32_e32 v45, 3, v5
	v_cndmask_b32_e32 v43, 0, v205, vcc
	v_cmp_lt_u32_e32 vcc, v5, v161
	v_or_b32_e32 v48, 8, v5
	v_or_b32_e32 v47, 9, v5
	v_cndmask_b32_e64 v44, v205, 0, vcc
	v_perm_b32 v146, v44, v39, s13
	v_or_b32_e32 v44, 17, v5
	v_or_b32_e32 v39, 18, v5
	v_cmp_gt_u32_e32 vcc, v44, v161
	v_or_b32_e32 v50, 10, v5
	v_or_b32_e32 v49, 11, v5
	v_cndmask_b32_e32 v44, 0, v205, vcc
	v_cmp_gt_u32_e32 vcc, v39, v161
	s_ashr_i32 s2, s2, 7
	s_mov_b32 s16, 0
	v_cndmask_b32_e32 v39, 0, v205, vcc
	v_cmp_gt_u32_e32 vcc, v46, v161
	v_and_b32_e32 v3, 63, v41
	s_add_i32 s28, s2, s24
	v_cndmask_b32_e32 v46, 0, v205, vcc
	v_cmp_gt_u32_e32 vcc, v45, v161
	s_nop 1
	v_cndmask_b32_e32 v45, 0, v205, vcc
	v_perm_b32 v147, v45, v46, s13
	v_or_b32_e32 v46, 19, v5
	v_or_b32_e32 v45, 24, v5
	v_cmp_gt_u32_e32 vcc, v46, v161
	s_nop 1
	v_cndmask_b32_e32 v46, 0, v205, vcc
	v_cmp_gt_u32_e32 vcc, v45, v161
	s_nop 1
	v_cndmask_b32_e32 v45, 0, v205, vcc
	v_cmp_gt_u32_e32 vcc, v48, v161
	s_nop 1
	v_cndmask_b32_e32 v48, 0, v205, vcc
	v_cmp_gt_u32_e32 vcc, v47, v161
	s_nop 1
	v_cndmask_b32_e32 v47, 0, v205, vcc
	v_perm_b32 v148, v47, v48, s13
	v_or_b32_e32 v47, 26, v5
	v_or_b32_e32 v48, 25, v5
	v_cmp_gt_u32_e32 vcc, v47, v161
	s_nop 1
	v_cndmask_b32_e32 v47, 0, v205, vcc
	v_cmp_gt_u32_e32 vcc, v48, v161
	s_nop 1
	v_cndmask_b32_e32 v48, 0, v205, vcc
	v_cmp_gt_u32_e32 vcc, v50, v161
	s_nop 1
	v_cndmask_b32_e32 v50, 0, v205, vcc
	v_cmp_gt_u32_e32 vcc, v49, v161
	s_nop 1
	v_cndmask_b32_e32 v49, 0, v205, vcc
	v_perm_b32 v149, v49, v50, s13
	v_or_b32_e32 v49, 27, v5
	v_cmp_gt_u32_e32 vcc, v49, v161
	s_nop 1
	v_cndmask_b32_e32 v49, 0, v205, vcc
	s_mul_i32 s0, s5, 52
	s_lshr_b32 s0, s0, 8
	s_mul_i32 s0, s0, 5
	s_sub_i32 s0, s5, s0
	s_and_b32 s0, s0, 0xff
	s_mul_i32 s5, s0, 0x2400
	v_add_u32_e32 v50, s5, v42
	s_mulk_i32 s0, 0x3000
	s_waitcnt vmcnt(11)
	ds_write_b128 v50, v[6:9]
	v_add_u32_e32 v6, s0, v40
	s_mul_i32 s0, s8, 52
	s_lshr_b32 s0, s0, 8
	s_mul_i32 s0, s0, 5
	s_sub_i32 s0, s8, s0
	s_and_b32 s0, s0, 0xff
	s_mul_i32 s5, s0, 0x2400
	s_waitcnt vmcnt(10)
	ds_write_b128 v6, v[10:13] offset:46080
	v_add_u32_e32 v6, s5, v42
	s_mulk_i32 s0, 0x3000
	s_waitcnt vmcnt(9)
	ds_write_b128 v6, v[14:17]
	v_add_u32_e32 v6, s0, v40
	s_mul_i32 s0, s9, 52
	s_lshr_b32 s0, s0, 8
	s_mul_i32 s0, s0, 5
	s_sub_i32 s0, s9, s0
	s_and_b32 s0, s0, 0xff
	s_mul_i32 s5, s0, 0x2400
	s_waitcnt vmcnt(8)
	ds_write_b128 v6, v[18:21] offset:46080
	v_add_u32_e32 v6, s5, v42
	s_mulk_i32 s0, 0x3000
	s_waitcnt vmcnt(7)
	ds_write_b128 v6, v[22:25]
	v_add_u32_e32 v6, s0, v40
	s_mul_i32 s0, s12, 0xd0
	s_lshr_b32 s0, s0, 8
	s_mul_i32 s0, s0, 5
	s_sub_i32 s0, s24, s0
	s_and_b32 s0, s0, 0xff
	s_mul_i32 s5, s0, 0x2400
	s_waitcnt vmcnt(6)
	ds_write_b128 v6, v[26:29] offset:46080
	v_add_u32_e32 v6, s5, v42
	s_mulk_i32 s0, 0x3000
	s_waitcnt vmcnt(5)
	ds_write_b128 v6, v[30:33]
	v_add_u32_e32 v6, s0, v40
	s_lshl_b32 s20, s28, 6
	s_waitcnt vmcnt(4)
	ds_write_b128 v6, v[34:37] offset:46080
	v_lshrrev_b32_e32 v6, 2, v41
	v_sub_u32_e32 v9, s20, v154
	v_and_or_b32 v6, v6, 3, v5
	v_add_u32_e32 v5, v9, v5
	v_add_u32_e32 v9, 32, v5
	v_cmp_gt_i32_e64 s[42:43], 0, v9
	v_add_u32_e32 v9, 33, v5
	v_cmp_gt_i32_e64 s[44:45], 0, v9
	v_add_u32_e32 v9, 34, v5
	v_cmp_gt_i32_e64 s[46:47], 0, v9
	v_add_u32_e32 v9, 35, v5
	v_cmp_gt_i32_e64 s[48:49], 0, v9
	v_add_u32_e32 v9, 40, v5
	v_cmp_gt_i32_e64 s[50:51], 0, v9
	v_add_u32_e32 v9, 41, v5
	v_cmp_gt_i32_e64 s[52:53], 0, v9
	v_add_u32_e32 v9, 42, v5
	v_cmp_gt_i32_e64 s[54:55], 0, v9
	v_add_u32_e32 v9, 43, v5
	v_cmp_gt_i32_e64 s[56:57], 0, v9
	v_add_u32_e32 v9, 48, v5
	v_cmp_gt_i32_e64 s[58:59], 0, v9
	v_add_u32_e32 v9, 49, v5
	v_cmp_gt_i32_e64 s[60:61], 0, v9
	v_add_u32_e32 v9, 50, v5
	v_cmp_gt_i32_e64 s[62:63], 0, v9
	v_add_u32_e32 v9, 51, v5
	v_cmp_gt_i32_e64 s[64:65], 0, v9
	v_add_u32_e32 v9, 56, v5
	v_cmp_gt_i32_e64 s[66:67], 0, v9
	v_add_u32_e32 v9, 57, v5
	v_cmp_gt_i32_e64 s[68:69], 0, v9
	v_add_u32_e32 v9, 58, v5
	v_cmp_gt_i32_e64 s[70:71], 0, v9
	v_add_u32_e32 v9, 59, v5
	v_cmp_gt_i32_e64 s[72:73], 0, v9
	v_add_u32_e32 v9, 1, v5
	v_cmp_gt_i32_e64 s[76:77], 0, v9
	v_add_u32_e32 v9, 2, v5
	v_cmp_gt_i32_e64 s[78:79], 0, v9
	v_add_u32_e32 v9, 3, v5
	v_cmp_gt_i32_e64 s[80:81], 0, v9
	v_add_u32_e32 v9, 8, v5
	v_cmp_gt_i32_e64 s[82:83], 0, v9
	v_add_u32_e32 v9, 9, v5
	v_cmp_gt_i32_e64 s[84:85], 0, v9
	v_add_u32_e32 v9, 10, v5
	v_cmp_gt_i32_e64 s[86:87], 0, v9
	v_add_u32_e32 v9, 11, v5
	v_cmp_gt_i32_e64 s[88:89], 0, v9
	v_add_u32_e32 v9, 16, v5
	v_cmp_gt_i32_e64 s[90:91], 0, v9
	v_add_u32_e32 v9, 17, v5
	v_cmp_gt_i32_e64 s[92:93], 0, v9
	v_add_u32_e32 v9, 18, v5
	v_cmp_gt_i32_e64 s[94:95], 0, v9
	v_add_u32_e32 v9, 19, v5
	v_cmp_gt_i32_e64 s[96:97], 0, v9
	v_add_u32_e32 v9, 24, v5
	s_lshl_b32 s0, s4, 2
	v_cmp_gt_i32_e64 s[4:5], 0, v9
	v_add_u32_e32 v9, 25, v5
	s_add_i32 s17, s0, 0
	v_mul_u32_u24_e32 v6, 0xc0, v6
	v_cmp_gt_i32_e64 s[74:75], 0, v5
	v_cmp_gt_i32_e64 s[6:7], 0, v9
	v_add_u32_e32 v9, 26, v5
	v_add_u32_e32 v5, 27, v5
	v_perm_b32 v152, v48, v45, s13
	v_perm_b32 v151, v46, v39, s13
	v_perm_b32 v153, v49, v47, s13
	v_perm_b32 v150, v44, v43, s13
	s_mul_i32 s0, s12, 0xc000
	s_mul_i32 s13, s2, 0x3000
	v_cmp_gt_i32_e64 s[10:11], 0, v5
	v_or_b32_e32 v5, s13, v6
	s_add_i32 s21, s0, 0
	s_mul_i32 s0, s12, 0x9000
	s_movk_i32 s13, 0x90
	v_lshlrev_b32_e32 v7, 1, v41
	v_lshlrev_b32_e32 v8, 3, v41
	s_add_i32 s12, s0, 0xffffdc00
	v_mul_lo_u32 v2, v2, s13
	v_and_b32_e32 v7, 32, v7
	v_and_b32_e32 v8, 24, v8
	v_add3_u32 v177, s12, v2, v4
	s_mul_i32 s12, s2, 0x2400
	v_cmp_eq_u32_e64 s[40:41], 0, v3
	v_mul_u32_u24_e32 v3, 0x90, v161
	v_or3_b32 v5, v5, v7, v8
	s_add_i32 s12, s12, s0
	v_mov_b32_e32 v14, v1
	v_mov_b32_e32 v15, v1
	v_and_or_b32 v16, v200, 64, v161
	v_cmp_gt_i32_e64 s[8:9], 0, v9
	v_add_u32_e32 v155, 0xde40, v5
	v_add_u32_e32 v162, 0xd840, v5
	v_add_u32_e32 v163, 0xde00, v5
	v_add_u32_e32 v164, 0xd800, v5
	v_add_u32_e32 v165, 0xd240, v5
	v_add_u32_e32 v166, 0xcc40, v5
	v_add_u32_e32 v167, 0xd200, v5
	v_add_u32_e32 v168, 0xcc00, v5
	v_add_u32_e32 v169, 0xc640, v5
	v_add_u32_e32 v170, 0xc040, v5
	v_add_u32_e32 v171, 0xc600, v5
	v_add_u32_e32 v172, 0xc000, v5
	v_add_u32_e32 v173, 0xba40, v5
	v_add_u32_e32 v174, 0xb440, v5
	v_add_u32_e32 v175, 0xba00, v5
	v_add_u32_e32 v176, 0xb400, v5
	v_add_u32_e32 v178, 0x8400, v38
	v_add3_u32 v179, s12, v3, v0
	v_mov_b32_e32 v0, v1
	v_mov_b32_e32 v2, v1
	v_mov_b32_e32 v3, v1
	v_mov_b32_e32 v4, v1
	v_mov_b32_e32 v5, v1
	v_mov_b32_e32 v6, v1
	v_mov_b32_e32 v7, v1
	v_mov_b32_e32 v8, v1
	v_mov_b32_e32 v9, v1
	v_mov_b32_e32 v10, v1
	v_mov_b32_e32 v11, v1
	v_mov_b32_e32 v12, v1
	v_mov_b32_e32 v13, v1
	v_lshlrev_b32_e32 v188, 2, v16
	v_mov_b64_e32 v[30:31], v[14:15]
	v_mov_b64_e32 v[46:47], v[14:15]
	s_add_i32 s17, s17, 0x1a400
	s_add_i32 s14, s24, -1
	s_mov_b64 s[30:31], 0
	v_mov_b32_e32 v48, 0
	s_mov_b32 s15, 0
	v_mov_b64_e32 v[28:29], v[12:13]
	v_mov_b64_e32 v[26:27], v[10:11]
	v_mov_b64_e32 v[24:25], v[8:9]
	v_mov_b64_e32 v[22:23], v[6:7]
	v_mov_b64_e32 v[20:21], v[4:5]
	v_mov_b64_e32 v[18:19], v[2:3]
	v_mov_b64_e32 v[16:17], v[0:1]
	v_mov_b64_e32 v[44:45], v[12:13]
	v_mov_b64_e32 v[42:43], v[10:11]
	v_mov_b64_e32 v[40:41], v[8:9]
	v_mov_b64_e32 v[38:39], v[6:7]
	v_mov_b64_e32 v[36:37], v[4:5]
	v_mov_b64_e32 v[34:35], v[2:3]
	v_mov_b64_e32 v[32:33], v[0:1]
	s_mov_b32 s29, 0
	s_waitcnt lgkmcnt(0)
	s_barrier

.LBB0_382:
	s_add_i32 s24, s2, s24
	s_cmp_lt_i32 s24, 0
	s_cselect_b64 s[34:35], -1, 0
	s_or_b64 s[34:35], s[34:35], s[30:31]
	s_and_b64 vcc, exec, s[34:35]
	s_cbranch_vccnz .LBB0_387
	s_mul_hi_u32 s25, s28, 0xcccccccd
	s_lshr_b32 s25, s25, 2
	s_mul_i32 s26, s25, 0xf000
	s_mul_i32 s25, s25, 0xb400
	v_subrev_u32_e32 v10, s25, v179
	v_subrev_u32_e32 v0, s26, v155
	v_subrev_u32_e32 v189, s26, v162
	v_subrev_u32_e32 v190, s26, v163
	v_subrev_u32_e32 v191, s26, v164
	v_subrev_u32_e32 v192, s26, v165
	v_subrev_u32_e32 v193, s26, v166
	v_subrev_u32_e32 v194, s26, v167
	v_subrev_u32_e32 v196, s26, v168
	v_subrev_u32_e32 v197, s26, v169
	v_subrev_u32_e32 v210, s26, v170
	v_subrev_u32_e32 v211, s26, v171
	v_subrev_u32_e32 v212, s26, v172
	v_subrev_u32_e32 v213, s26, v173
	v_subrev_u32_e32 v214, s26, v174
	v_subrev_u32_e32 v215, s26, v175
	v_subrev_u32_e32 v216, s26, v176
	s_cmp_lg_u32 s29, 0
	v_add_u32_e32 v217, 0, v10
	s_cbranch_scc0 .LBB0_388
	ds_read_b128 v[50:53], v217 offset:4608
	ds_read_b128 v[70:73], v217 offset:4640
	ds_read_b128 v[66:69], v217
	ds_read_b128 v[84:87], v217 offset:32
	ds_read_b128 v[74:77], v217 offset:4672
	ds_read_b128 v[88:91], v217 offset:4704
	ds_read_b128 v[80:83], v217 offset:64
	ds_read_b128 v[10:13], v217 offset:96
	s_waitcnt lgkmcnt(7)
	v_mfma_f32_32x32x16_bf16 v[50:65], v[50:53], v[130:133], 0
	s_waitcnt lgkmcnt(6)
	v_mfma_f32_32x32x16_bf16 v[50:65], v[70:73], v[134:137], v[50:65]
	s_waitcnt lgkmcnt(3)
	v_mfma_f32_32x32x16_bf16 v[50:65], v[74:77], v[138:141], v[50:65]
	s_waitcnt lgkmcnt(2)
	v_mfma_f32_32x32x16_bf16 v[50:65], v[88:91], v[142:145], v[50:65]
	s_nop 11
	v_max_f32_e32 v14, v50, v50
	v_min_f32_e32 v14, 0x42fc0000, v14
	v_exp_f32_e32 v15, v14
	s_nop 0
	v_add_f32_e32 v15, 1.0, v15
	v_log_f32_e32 v49, v15
	v_max_f32_e32 v15, v51, v51
	v_max_f32_e32 v51, v52, v52
	v_min_f32_e32 v51, 0x42fc0000, v51
	v_exp_f32_e32 v52, v51
	v_min_f32_e32 v15, 0x42fc0000, v15
	v_exp_f32_e32 v50, v15
	v_sub_f32_e32 v14, v14, v49
	v_add_f32_e32 v52, 1.0, v52
	v_log_f32_e32 v52, v52
	v_add_f32_e32 v50, 1.0, v50
	v_log_f32_e32 v50, v50
	v_sub_f32_e32 v218, v51, v52
	v_max_f32_e32 v51, v53, v53
	v_min_f32_e32 v51, 0x42fc0000, v51
	v_exp_f32_e32 v53, v51
	v_sub_f32_e32 v15, v15, v50
	v_add_f32_e32 v53, 1.0, v53
	v_log_f32_e32 v53, v53
	s_nop 0
	v_sub_f32_e32 v219, v51, v53
	v_max_f32_e32 v51, v54, v54
	v_min_f32_e32 v51, 0x42fc0000, v51
	v_exp_f32_e32 v54, v51
	s_nop 0
	v_add_f32_e32 v54, 1.0, v54
	v_log_f32_e32 v54, v54
	s_nop 0
	v_sub_f32_e32 v220, v51, v54
	v_max_f32_e32 v51, v55, v55
	v_min_f32_e32 v51, 0x42fc0000, v51
	v_exp_f32_e32 v55, v51
	s_nop 0
	v_add_f32_e32 v55, 1.0, v55
	v_log_f32_e32 v55, v55
	s_nop 0
	v_sub_f32_e32 v221, v51, v55
	v_max_f32_e32 v51, v56, v56
	v_min_f32_e32 v51, 0x42fc0000, v51
	v_exp_f32_e32 v56, v51
	s_nop 0
	v_add_f32_e32 v56, 1.0, v56
	v_log_f32_e32 v56, v56
	s_nop 0
	v_sub_f32_e32 v222, v51, v56
	v_max_f32_e32 v51, v57, v57
	v_min_f32_e32 v51, 0x42fc0000, v51
	v_exp_f32_e32 v57, v51
	s_nop 0
	v_add_f32_e32 v57, 1.0, v57
	v_log_f32_e32 v57, v57
	s_nop 0
	v_sub_f32_e32 v223, v51, v57
	v_max_f32_e32 v51, v58, v58
	v_min_f32_e32 v51, 0x42fc0000, v51
	v_exp_f32_e32 v58, v51
	s_nop 0
	v_add_f32_e32 v58, 1.0, v58
	v_log_f32_e32 v58, v58
	s_nop 0
	v_sub_f32_e32 v224, v51, v58
	v_max_f32_e32 v51, v59, v59
	v_min_f32_e32 v51, 0x42fc0000, v51
	v_exp_f32_e32 v59, v51
	s_nop 0
	v_add_f32_e32 v59, 1.0, v59
	v_log_f32_e32 v59, v59
	s_nop 0
	v_sub_f32_e32 v225, v51, v59
	v_max_f32_e32 v51, v60, v60
	v_min_f32_e32 v51, 0x42fc0000, v51
	v_exp_f32_e32 v60, v51
	s_nop 0
	v_add_f32_e32 v60, 1.0, v60
	v_log_f32_e32 v60, v60
	s_nop 0
	v_sub_f32_e32 v226, v51, v60
	v_max_f32_e32 v51, v61, v61
	v_min_f32_e32 v51, 0x42fc0000, v51
	v_exp_f32_e32 v61, v51
	s_nop 0
	v_add_f32_e32 v61, 1.0, v61
	v_log_f32_e32 v61, v61
	s_nop 0
	v_sub_f32_e32 v227, v51, v61
	v_max_f32_e32 v51, v62, v62
	v_min_f32_e32 v51, 0x42fc0000, v51
	v_exp_f32_e32 v62, v51
	s_nop 0
	v_add_f32_e32 v62, 1.0, v62
	v_log_f32_e32 v62, v62
	s_nop 0
	v_sub_f32_e32 v228, v51, v62
	v_max_f32_e32 v51, v63, v63
	v_min_f32_e32 v51, 0x42fc0000, v51
	v_exp_f32_e32 v63, v51
	s_nop 0
	v_add_f32_e32 v63, 1.0, v63
	v_log_f32_e32 v63, v63
	s_nop 0
	v_sub_f32_e32 v229, v51, v63
	v_max_f32_e32 v51, v64, v64
	v_min_f32_e32 v51, 0x42fc0000, v51
	v_exp_f32_e32 v64, v51
	s_nop 0
	v_add_f32_e32 v64, 1.0, v64
	v_log_f32_e32 v88, v64
	s_nop 0
	v_sub_f32_e32 v230, v51, v88
	v_max_f32_e32 v51, v65, v65
	v_min_f32_e32 v51, 0x42fc0000, v51
	v_exp_f32_e32 v64, v51
	s_nop 0
	v_add_f32_e32 v64, 1.0, v64
	v_log_f32_e32 v89, v64
	v_mfma_f32_32x32x16_bf16 v[64:79], v[66:69], v[130:133], 0
	v_sub_f32_e32 v231, v51, v89
	v_mov_b32_e32 v51, v48
	v_mfma_f32_32x32x16_bf16 v[64:79], v[84:87], v[134:137], v[64:79]
	v_cvt_pk_bf16_f32 v86, v62, v63
	v_mov_b32_e32 v62, v48
	v_mov_b32_e32 v63, v48
	v_cvt_pk_bf16_f32 v84, v58, v59
	v_cvt_pk_bf16_f32 v85, v60, v61
	v_mov_b32_e32 v58, v48
	v_mov_b32_e32 v59, v48
	s_waitcnt lgkmcnt(1)
	v_mfma_f32_32x32x16_bf16 v[64:79], v[80:83], v[138:141], v[64:79]
	v_cvt_pk_bf16_f32 v80, v49, v50
	v_cvt_pk_bf16_f32 v81, v52, v53
	v_cvt_pk_bf16_f32 v82, v54, v55
	v_cvt_pk_bf16_f32 v83, v56, v57
	v_mov_b32_e32 v49, v48
	v_mov_b32_e32 v50, v48
	v_mov_b32_e32 v52, v48
	v_mov_b32_e32 v53, v48
	v_mov_b32_e32 v54, v48
	v_mov_b32_e32 v55, v48
	v_mov_b32_e32 v56, v48
	v_mov_b32_e32 v57, v48
	v_mov_b32_e32 v60, v48
	v_mov_b32_e32 v61, v48
	v_mov_b64_e32 v[112:113], v[62:63]
	v_mov_b64_e32 v[110:111], v[60:61]
	v_mov_b64_e32 v[108:109], v[58:59]
	v_mov_b64_e32 v[106:107], v[56:57]
	v_mov_b64_e32 v[104:105], v[54:55]
	v_mov_b64_e32 v[102:103], v[52:53]
	v_mov_b64_e32 v[100:101], v[50:51]
	v_mov_b64_e32 v[98:99], v[48:49]
	v_cvt_pk_bf16_f32 v87, v88, v89
	s_waitcnt lgkmcnt(0)
	v_mfma_f32_32x32x16_bf16 v[64:79], v[10:13], v[142:145], v[64:79]
	v_mfma_f32_32x32x16_bf16 v[98:113], v[146:149], v[80:83], v[98:113]
	v_mfma_f32_32x32x16_bf16 v[98:113], v[150:153], v[84:87], v[98:113]
	s_nop 9
	v_max_f32_e32 v10, v64, v64
	v_min_f32_e32 v232, 0x42fc0000, v10
	v_max_f32_e32 v11, v65, v65
	v_exp_f32_e32 v10, v232
	v_min_f32_e32 v233, 0x42fc0000, v11
	v_exp_f32_e32 v11, v233
	v_max_f32_e32 v12, v67, v67
	v_add_f32_e32 v10, 1.0, v10
	v_log_f32_e32 v234, v10
	v_add_f32_e32 v10, 1.0, v11
	v_max_f32_e32 v11, v66, v66
	v_min_f32_e32 v235, 0x42fc0000, v11
	v_exp_f32_e32 v11, v235
	v_min_f32_e32 v236, 0x42fc0000, v12
	v_exp_f32_e32 v12, v236
	v_log_f32_e32 v237, v10
	v_add_f32_e32 v10, 1.0, v11
	v_max_f32_e32 v11, v68, v68
	v_log_f32_e32 v238, v10
	v_add_f32_e32 v10, 1.0, v12
	v_min_f32_e32 v239, 0x42fc0000, v11
	v_max_f32_e32 v12, v69, v69
	v_exp_f32_e32 v11, v239
	v_min_f32_e32 v240, 0x42fc0000, v12
	v_exp_f32_e32 v12, v240
	v_log_f32_e32 v241, v10
	v_add_f32_e32 v10, 1.0, v11
	v_max_f32_e32 v11, v70, v70
	v_log_f32_e32 v242, v10
	v_add_f32_e32 v10, 1.0, v12
	v_min_f32_e32 v243, 0x42fc0000, v11
	v_max_f32_e32 v12, v71, v71
	v_exp_f32_e32 v11, v243
	v_min_f32_e32 v244, 0x42fc0000, v12
	v_exp_f32_e32 v12, v244
	v_log_f32_e32 v245, v10
	v_add_f32_e32 v10, 1.0, v11
	v_max_f32_e32 v11, v72, v72
	v_log_f32_e32 v246, v10
	v_add_f32_e32 v10, 1.0, v12
	v_min_f32_e32 v247, 0x42fc0000, v11
	v_max_f32_e32 v12, v73, v73
	v_exp_f32_e32 v11, v247
	v_min_f32_e32 v248, 0x42fc0000, v12
	v_exp_f32_e32 v12, v248
	v_log_f32_e32 v249, v10
	v_add_f32_e32 v10, 1.0, v11
	v_max_f32_e32 v11, v74, v74
	v_log_f32_e32 v250, v10
	v_add_f32_e32 v10, 1.0, v12
	v_min_f32_e32 v251, 0x42fc0000, v11
	v_max_f32_e32 v12, v75, v75
	v_exp_f32_e32 v11, v251
	v_min_f32_e32 v202, 0x42fc0000, v12
	v_exp_f32_e32 v12, v202
	v_log_f32_e32 v203, v10
	v_add_f32_e32 v10, 1.0, v11
	v_max_f32_e32 v11, v76, v76
	v_log_f32_e32 v199, v10
	v_add_f32_e32 v10, 1.0, v12
	v_min_f32_e32 v207, 0x42fc0000, v11
	v_max_f32_e32 v12, v77, v77
	v_exp_f32_e32 v11, v207
	v_min_f32_e32 v201, 0x42fc0000, v12
	v_exp_f32_e32 v12, v201
	v_log_f32_e32 v186, v10
	v_add_f32_e32 v10, 1.0, v11
	v_max_f32_e32 v11, v78, v78
	v_log_f32_e32 v187, v10
	v_add_f32_e32 v10, 1.0, v12
	v_min_f32_e32 v198, 0x42fc0000, v11
	v_max_f32_e32 v12, v79, v79
	v_exp_f32_e32 v11, v198
	v_min_f32_e32 v208, 0x42fc0000, v12
	v_exp_f32_e32 v12, v208
	v_log_f32_e32 v184, v10
	v_add_f32_e32 v10, 1.0, v11
	v_log_f32_e32 v185, v10
	v_add_f32_e32 v10, 1.0, v12
	v_log_f32_e32 v180, v10
	v_cvt_pk_bf16_f32 v12, v242, v245
	v_cvt_pk_bf16_f32 v13, v246, v249
	v_cvt_pk_bf16_f32 v50, v250, v203
	v_cvt_pk_bf16_f32 v51, v199, v186
	v_cvt_pk_bf16_f32 v52, v187, v184
	v_cvt_pk_bf16_f32 v53, v185, v180
	v_cvt_pk_bf16_f32 v10, v234, v237
	v_cvt_pk_bf16_f32 v11, v238, v241
	v_lshlrev_b32_e32 v49, 16, v80
	v_add_f32_e32 v49, v98, v49
	ds_bpermute_b32 v114, v188, v49
	s_add_i32 s25, s21, s16
	v_add_u32_e32 v49, s25, v212
	s_waitcnt lgkmcnt(0)
	v_mov_b32_e32 v115, v114
	v_mov_b32_e32 v116, v114
	v_mov_b32_e32 v117, v114
	v_mov_b32_e32 v118, v114
	v_mov_b32_e32 v119, v114
	v_mov_b32_e32 v120, v114
	v_mov_b32_e32 v121, v114
	v_mov_b32_e32 v122, v114
	v_mov_b32_e32 v123, v114
	v_mov_b32_e32 v124, v114
	v_mov_b32_e32 v125, v114
	v_mov_b32_e32 v126, v114
	v_mov_b32_e32 v127, v114
	v_mov_b32_e32 v128, v114
	v_mov_b32_e32 v129, v114
	v_mov_b64_e32 v[82:83], v[114:115]
	v_mov_b64_e32 v[84:85], v[116:117]
	v_mov_b64_e32 v[86:87], v[118:119]
	v_mov_b64_e32 v[88:89], v[120:121]
	v_mov_b64_e32 v[90:91], v[122:123]
	v_mov_b64_e32 v[92:93], v[124:125]
	v_mov_b64_e32 v[94:95], v[126:127]
	v_mov_b64_e32 v[96:97], v[128:129]
	s_nop 1
	v_mfma_f32_32x32x16_bf16 v[82:97], v[146:149], v[10:13], v[82:97]
	v_add_u32_e32 v12, s25, v196
	ds_read_b64_tr_b16 v[66:67], v12
	v_add_u32_e32 v12, s25, v194
	ds_read_b64_tr_b16 v[68:69], v12
	v_add_u32_e32 v12, s25, v193
	ds_read_b64_tr_b16 v[116:117], v12
	v_add_u32_e32 v12, s25, v192
	v_mfma_f32_32x32x16_bf16 v[82:97], v[150:153], v[50:53], v[82:97]
	ds_read_b64_tr_b16 v[118:119], v12
	v_add_u32_e32 v12, s25, v191
	ds_read_b64_tr_b16 v[120:121], v12
	v_add_u32_e32 v12, s25, v190
	ds_read_b64_tr_b16 v[122:123], v12
	v_add_u32_e32 v12, s25, v189
	ds_read_b64_tr_b16 v[124:125], v12
	v_add_u32_e32 v12, s25, v0
	ds_read_b64_tr_b16 v[126:127], v12
	v_add_u32_e32 v11, s25, v216
	v_sub_f32_e32 v12, v14, v98
	v_sub_f32_e32 v13, v15, v99
	v_sub_f32_e32 v14, v218, v100
	v_sub_f32_e32 v15, v219, v101
	v_sub_f32_e32 v50, v220, v102
	v_sub_f32_e32 v51, v221, v103
	v_sub_f32_e32 v52, v222, v104
	v_sub_f32_e32 v53, v223, v105
	v_sub_f32_e32 v54, v224, v106
	v_sub_f32_e32 v55, v225, v107
	v_sub_f32_e32 v56, v226, v108
	v_sub_f32_e32 v57, v227, v109
	v_sub_f32_e32 v58, v228, v110
	v_sub_f32_e32 v59, v229, v111
	v_sub_f32_e32 v60, v230, v112
	v_sub_f32_e32 v61, v231, v113
	v_exp_f32_e32 v12, v12
	v_exp_f32_e32 v13, v13
	v_exp_f32_e32 v14, v14
	v_exp_f32_e32 v15, v15
	v_exp_f32_e32 v50, v50
	v_exp_f32_e32 v51, v51
	v_exp_f32_e32 v52, v52
	v_exp_f32_e32 v53, v53
	v_exp_f32_e32 v54, v54
	v_exp_f32_e32 v55, v55
	v_exp_f32_e32 v56, v56
	v_exp_f32_e32 v57, v57
	v_exp_f32_e32 v58, v58
	v_exp_f32_e32 v59, v59
	v_exp_f32_e32 v60, v60
	v_exp_f32_e32 v61, v61
	v_cvt_pk_bf16_f32 v12, v12, v13
	v_cvt_pk_bf16_f32 v13, v14, v15
	v_cvt_pk_bf16_f32 v14, v50, v51
	v_cvt_pk_bf16_f32 v15, v52, v53
	v_cvt_pk_bf16_f32 v98, v54, v55
	v_cvt_pk_bf16_f32 v99, v56, v57
	v_cvt_pk_bf16_f32 v100, v58, v59
	v_cvt_pk_bf16_f32 v101, v60, v61
	s_waitcnt lgkmcnt(6)
	v_mfma_f32_32x32x16_bf16 v[50:65], v[66:69], v[12:15], v[32:47]
	ds_read_b64_tr_b16 v[102:103], v11
	v_add_u32_e32 v11, s25, v215
	ds_read_b64_tr_b16 v[104:105], v11
	v_add_u32_e32 v11, s25, v214
	s_waitcnt lgkmcnt(6)
	v_mfma_f32_32x32x16_bf16 v[66:81], v[116:119], v[12:15], v[16:31]
	s_waitcnt lgkmcnt(4)
	v_mfma_f32_32x32x16_bf16 v[50:65], v[120:123], v[98:101], v[50:65]
	s_waitcnt lgkmcnt(2)
	v_mfma_f32_32x32x16_bf16 v[66:81], v[124:127], v[98:101], v[66:81]
	ds_read_b64_tr_b16 v[98:99], v11
	v_add_u32_e32 v11, s25, v213
	ds_read_b64_tr_b16 v[100:101], v11
	ds_read_b64_tr_b16 v[12:13], v49
	v_add_u32_e32 v11, s25, v211
	ds_read_b64_tr_b16 v[14:15], v11
	v_add_u32_e32 v11, s25, v210
	ds_read_b64_tr_b16 v[106:107], v11
	v_add_u32_e32 v11, s25, v197
	ds_read_b64_tr_b16 v[108:109], v11
	v_lshlrev_b32_e32 v10, 16, v10
	v_add_f32_e32 v10, v82, v10
	ds_bpermute_b32 v49, v188, v10
	v_cmp_lt_f32_e32 vcc, s33, v114
	s_cmp_eq_u64 vcc, exec
	s_cbranch_scc1 .LBB0_386
	v_sub_f32_e32 v10, v232, v234
	v_sub_f32_e32 v110, v235, v238
	v_sub_f32_e32 v11, v233, v237
	v_sub_f32_e32 v111, v236, v241
	v_sub_f32_e32 v10, v10, v82
	v_sub_f32_e32 v82, v110, v84
	v_sub_f32_e32 v112, v239, v242
	v_sub_f32_e32 v11, v11, v83
	v_exp_f32_e32 v83, v82
	v_sub_f32_e32 v82, v111, v85
	v_sub_f32_e32 v113, v240, v245
	v_exp_f32_e32 v84, v82
	v_sub_f32_e32 v82, v112, v86
	v_sub_f32_e32 v114, v243, v246
	v_exp_f32_e32 v85, v82
	v_sub_f32_e32 v82, v113, v87
	v_sub_f32_e32 v115, v244, v249
	v_exp_f32_e32 v86, v82
	v_sub_f32_e32 v82, v114, v88
	v_sub_f32_e32 v116, v247, v250
	v_exp_f32_e32 v87, v82
	v_sub_f32_e32 v82, v115, v89
	v_sub_f32_e32 v117, v248, v203
	v_exp_f32_e32 v88, v82
	v_sub_f32_e32 v82, v116, v90
	v_sub_f32_e32 v118, v251, v199
	v_exp_f32_e32 v89, v82
	v_sub_f32_e32 v82, v117, v91
	v_sub_f32_e32 v119, v202, v186
	v_exp_f32_e32 v90, v82
	v_sub_f32_e32 v82, v118, v92
	v_sub_f32_e32 v120, v207, v187
	v_exp_f32_e32 v91, v82
	v_sub_f32_e32 v82, v119, v93
	v_sub_f32_e32 v121, v201, v184
	v_exp_f32_e32 v10, v10
	v_exp_f32_e32 v11, v11
	v_exp_f32_e32 v92, v82
	v_sub_f32_e32 v82, v120, v94
	v_sub_f32_e32 v122, v198, v185
	v_exp_f32_e32 v93, v82
	v_sub_f32_e32 v82, v121, v95
	v_sub_f32_e32 v123, v208, v180
	v_exp_f32_e32 v94, v82
	v_sub_f32_e32 v82, v122, v96
	v_exp_f32_e32 v95, v82
	v_sub_f32_e32 v82, v123, v97
	v_exp_f32_e32 v96, v82
	v_cvt_pk_bf16_f32 v82, v10, v11
	v_cvt_pk_bf16_f32 v83, v83, v84
	v_cvt_pk_bf16_f32 v84, v85, v86
	v_cvt_pk_bf16_f32 v85, v87, v88
	v_cvt_pk_bf16_f32 v86, v89, v90
	v_cvt_pk_bf16_f32 v87, v91, v92
	s_waitcnt lgkmcnt(7)
	v_mfma_f32_32x32x16_bf16 v[50:65], v[102:105], v[82:85], v[50:65]
	v_cvt_pk_bf16_f32 v88, v93, v94
	v_cvt_pk_bf16_f32 v89, v95, v96
	s_waitcnt lgkmcnt(5)
	v_mfma_f32_32x32x16_bf16 v[66:81], v[98:101], v[82:85], v[66:81]
	s_waitcnt lgkmcnt(3)
	v_mfma_f32_32x32x16_bf16 v[50:65], v[12:15], v[86:89], v[50:65]
	s_waitcnt lgkmcnt(1)
	v_mfma_f32_32x32x16_bf16 v[66:81], v[106:109], v[86:89], v[66:81]

.LBB0_395:
	s_add_i32 s25, s21, s16
	s_waitcnt lgkmcnt(3)
	v_add_u32_e32 v14, s25, v216
	v_add_u32_e32 v64, s25, v213
	v_add_u32_e32 v15, s25, v215
	v_add_u32_e32 v48, s25, v214
	ds_read_b64_tr_b16 v[58:59], v14
	ds_read_b64_tr_b16 v[60:61], v15
	ds_read_b64_tr_b16 v[62:63], v48
	ds_read_b64_tr_b16 v[64:65], v64
	v_add_u32_e32 v14, s25, v212
	v_add_u32_e32 v76, s25, v197
	v_add_u32_e32 v15, s25, v211
	v_add_u32_e32 v48, s25, v210
	ds_read_b64_tr_b16 v[70:71], v14
	ds_read_b64_tr_b16 v[72:73], v15
	ds_read_b64_tr_b16 v[74:75], v48
	ds_read_b64_tr_b16 v[76:77], v76
	v_add_u32_e32 v14, s25, v196
	v_add_u32_e32 v84, s25, v192
	v_add_u32_e32 v15, s25, v194
	v_add_u32_e32 v48, s25, v193
	ds_read_b64_tr_b16 v[78:79], v14
	ds_read_b64_tr_b16 v[80:81], v15
	ds_read_b64_tr_b16 v[82:83], v48
	ds_read_b64_tr_b16 v[84:85], v84
	v_add_u32_e32 v14, s25, v191
	v_add_u32_e32 v15, s25, v190
	v_add_u32_e32 v48, s25, v189
	v_add_u32_e32 v0, s25, v0
	ds_read_b64_tr_b16 v[86:87], v14
	ds_read_b64_tr_b16 v[88:89], v15
	ds_read_b64_tr_b16 v[90:91], v48
	ds_read_b64_tr_b16 v[92:93], v0
	s_waitcnt lgkmcnt(14)
	v_mfma_f32_32x32x16_bf16 v[32:47], v[58:61], v[54:57], v[32:47]
	s_waitcnt lgkmcnt(12)
	v_mfma_f32_32x32x16_bf16 v[16:31], v[62:65], v[54:57], v[16:31]
	s_waitcnt lgkmcnt(10)
	v_mfma_f32_32x32x16_bf16 v[32:47], v[70:73], v[50:53], v[32:47]
	s_waitcnt lgkmcnt(8)
	v_mfma_f32_32x32x16_bf16 v[16:31], v[74:77], v[50:53], v[16:31]
	s_waitcnt lgkmcnt(6)
	v_mfma_f32_32x32x16_bf16 v[32:47], v[78:81], v[66:69], v[32:47]
	s_waitcnt lgkmcnt(4)
	v_mfma_f32_32x32x16_bf16 v[16:31], v[82:85], v[66:69], v[16:31]
	s_waitcnt lgkmcnt(2)
	v_mfma_f32_32x32x16_bf16 v[32:47], v[86:89], v[10:13], v[32:47]
	s_waitcnt lgkmcnt(0)
	v_mfma_f32_32x32x16_bf16 v[16:31], v[90:93], v[10:13], v[16:31]
	s_nop 9
	v_mov_b64_e32 v[64:65], v[46:47]
	v_mov_b64_e32 v[62:63], v[44:45]
	v_mov_b64_e32 v[60:61], v[42:43]
	v_mov_b64_e32 v[58:59], v[40:41]
	v_mov_b64_e32 v[56:57], v[38:39]
	v_mov_b64_e32 v[54:55], v[36:37]
	v_mov_b64_e32 v[52:53], v[34:35]
	v_mov_b64_e32 v[80:81], v[30:31]
	v_mov_b64_e32 v[50:51], v[32:33]
	v_mov_b64_e32 v[78:79], v[28:29]
	v_mov_b64_e32 v[76:77], v[26:27]
	v_mov_b64_e32 v[74:75], v[24:25]
	v_mov_b64_e32 v[72:73], v[22:23]
	v_mov_b64_e32 v[70:71], v[20:21]
	v_mov_b64_e32 v[68:69], v[18:19]
	v_mov_b64_e32 v[66:67], v[16:17]
